# XCD-local-barriers-for-seams-3-4,5-6,11-12,13-14-with-runtime-placement-check
# speedup vs baseline: 1.0629x; 1.0064x over previous
_Z8mega_fwd4Args:
	s_load_dwordx2 s[94:95], s[0:1], 0xb8
	s_mov_b32 s100, 0
	s_load_dwordx4 s[84:87], s[0:1], 0xa0
	s_load_dwordx8 s[4:11], s[0:1], 0x80
	s_mov_b32 s92, s2
	s_mov_b32 s14, s92
	s_waitcnt lgkmcnt(0)
	v_writelane_b32 v252, s4, 0
	s_nop 1
	v_writelane_b32 v252, s5, 1
	v_writelane_b32 v252, s6, 2
	v_writelane_b32 v252, s7, 3
	v_writelane_b32 v252, s8, 4
	v_writelane_b32 v252, s9, 5
	v_writelane_b32 v252, s10, 6
	v_writelane_b32 v252, s11, 7
	s_add_u32 s4, s0, 0xb8
	s_addc_u32 s5, s1, 0
	s_and_b32 s2, s94, 7
	s_cmp_lg_u32 s2, 0
	s_cbranch_scc1 .LBB0_2
	s_ashr_i32 s3, s92, 31
	s_lshr_b32 s3, s3, 29
	s_add_i32 s3, s92, s3
	s_ashr_i32 s6, s3, 3
	s_and_b32 s3, s3, -8
	s_ashr_i32 s2, s94, 3
	s_sub_i32 s3, s92, s3
	s_mul_i32 s2, s2, s3
	s_add_i32 s14, s2, s6

.LBB0_18:
	s_or_b64 exec, exec, s[6:7]
	s_load_dwordx16 s[36:51], s[0:1], 0x0
	s_load_dwordx16 s[16:31], s[0:1], 0x40
	s_add_u32 s0, s86, 0xd400000
	s_barrier
	s_waitcnt lgkmcnt(0)
	s_getreg_b32 s3, hwreg(HW_REG_XCC_ID, 0, 4)
	v_writelane_b32 v252, s16, 8
	s_addc_u32 s1, s87, 0
	s_and_b32 s3, s3, 15
	v_writelane_b32 v252, s17, 9
	v_writelane_b32 v252, s18, 10
	v_writelane_b32 v252, s19, 11
	v_writelane_b32 v252, s20, 12
	v_writelane_b32 v252, s21, 13
	v_writelane_b32 v252, s22, 14
	v_writelane_b32 v252, s23, 15
	v_writelane_b32 v252, s24, 16
	v_writelane_b32 v252, s25, 17
	v_writelane_b32 v252, s26, 18
	v_writelane_b32 v252, s27, 19
	v_writelane_b32 v252, s28, 20
	v_writelane_b32 v252, s29, 21
	v_writelane_b32 v252, s30, 22
	v_writelane_b32 v252, s31, 23
	v_cmp_eq_u32_e64 s[4:5], 0, v224
	s_mov_b64 s[20:21], exec
	s_nop 0
	v_writelane_b32 v252, s4, 24
	s_nop 1
	v_writelane_b32 v252, s5, 25
	s_and_b64 s[4:5], s[20:21], s[4:5]
	s_mov_b64 exec, s[4:5]
	s_cbranch_execz .LBB0_21
	s_mov_b64 s[22:23], exec
	v_mbcnt_lo_u32_b32 v0, s22, 0
	v_mbcnt_hi_u32_b32 v0, s23, v0
	v_cmp_eq_u32_e32 vcc, 0, v0
	s_and_b64 s[4:5], exec, vcc
	s_mov_b64 exec, s[4:5]
	s_cbranch_execz .LBB0_21
	s_and_b32 s4, s92, 7
	s_lshl_b32 s4, s4, 6
	v_mov_b32_e32 v2, s4
	s_lshl_b32 s5, 1, s3
	v_mov_b32_e32 v3, s5
	global_atomic_or v3, v2, v3, s[0:1] sc0
	s_waitcnt vmcnt(0)
	s_lshl_b32 s4, s3, 8
	s_bcnt1_i32_b64 s5, s[22:23]
	v_mov_b32_e32 v0, s4
	v_mov_b32_e32 v1, s5
	global_atomic_add v0, v1, s[0:1] offset:1024

.LBB0_594:
	v_readlane_b32 s4, v253, 35
	v_readlane_b32 s5, v253, 36
	v_cmp_ne_u32_e32 vcc, 0, v15
	v_readlane_b32 s2, v251, 33
	v_cndmask_b32_e64 v16, 0, v15, s[4:5]
	v_readlane_b32 s4, v253, 33
	v_readlane_b32 s5, v253, 34
	v_cndmask_b32_e64 v15, 0, 1, vcc
	v_cmp_ne_u32_e32 vcc, 0, v0
	v_cndmask_b32_e64 v16, v16, v0, s[4:5]
	v_readlane_b32 s4, v253, 31
	v_readlane_b32 s5, v253, 32
	v_addc_co_u32_e32 v0, vcc, 0, v15, vcc
	s_nop 0
	v_cndmask_b32_e64 v16, v16, v1, s[4:5]
	v_readlane_b32 s4, v253, 29
	v_readlane_b32 s5, v253, 30
	v_cmp_ne_u32_e32 vcc, 0, v1
	s_nop 0
	v_cndmask_b32_e64 v16, v16, v2, s[4:5]
	v_readlane_b32 s4, v253, 27
	v_readlane_b32 s5, v253, 28
	v_cndmask_b32_e64 v1, 0, 1, vcc
	v_cmp_ne_u32_e32 vcc, 0, v2
	v_cndmask_b32_e64 v16, v16, v3, s[4:5]
	v_readlane_b32 s4, v253, 25
	v_readlane_b32 s5, v253, 26
	v_addc_co_u32_e32 v0, vcc, v0, v1, vcc
	s_nop 0
	v_cndmask_b32_e64 v16, v16, v4, s[4:5]
	v_readlane_b32 s4, v253, 23
	v_readlane_b32 s5, v253, 24
	v_cmp_ne_u32_e32 vcc, 0, v3
	s_nop 0
	v_cndmask_b32_e64 v16, v16, v5, s[4:5]
	v_readlane_b32 s4, v253, 21
	v_readlane_b32 s5, v253, 22
	v_cndmask_b32_e64 v1, 0, 1, vcc
	v_cmp_ne_u32_e32 vcc, 0, v4
	v_cndmask_b32_e64 v16, v16, v6, s[4:5]
	v_readlane_b32 s4, v253, 19
	v_readlane_b32 s5, v253, 20
	v_addc_co_u32_e32 v0, vcc, v0, v1, vcc
	s_nop 0
	v_cndmask_b32_e64 v16, v16, v7, s[4:5]
	v_readlane_b32 s4, v253, 17
	v_readlane_b32 s5, v253, 18
	v_cmp_ne_u32_e32 vcc, 0, v5
	s_nop 0
	v_cndmask_b32_e64 v16, v16, v8, s[4:5]
	v_readlane_b32 s4, v253, 15
	v_cndmask_b32_e64 v1, 0, 1, vcc
	v_cmp_ne_u32_e32 vcc, 0, v6
	v_readlane_b32 s5, v253, 16
	s_nop 0
	v_addc_co_u32_e32 v0, vcc, v0, v1, vcc
	v_cndmask_b32_e64 v16, v16, v9, s[4:5]
	v_readlane_b32 s4, v253, 13
	v_cmp_ne_u32_e32 vcc, 0, v7
	v_readlane_b32 s5, v253, 14
	s_nop 0
	v_cndmask_b32_e64 v1, 0, 1, vcc
	v_cmp_ne_u32_e32 vcc, 0, v8
	v_cndmask_b32_e64 v16, v16, v10, s[4:5]
	v_readlane_b32 s4, v253, 11
	v_addc_co_u32_e32 v0, vcc, v0, v1, vcc
	v_readlane_b32 s5, v253, 12
	v_cmp_ne_u32_e32 vcc, 0, v9
	s_nop 0
	v_cndmask_b32_e64 v16, v16, v11, s[4:5]
	v_readlane_b32 s4, v253, 9
	v_cndmask_b32_e64 v1, 0, 1, vcc
	v_cmp_ne_u32_e32 vcc, 0, v10
	v_readlane_b32 s5, v253, 10
	s_nop 0
	v_addc_co_u32_e32 v0, vcc, v0, v1, vcc
	v_cndmask_b32_e64 v16, v16, v12, s[4:5]
	v_readlane_b32 s4, v253, 7
	v_cmp_ne_u32_e32 vcc, 0, v11
	v_readlane_b32 s5, v253, 8
	s_nop 0
	v_cndmask_b32_e64 v1, 0, 1, vcc
	v_cmp_ne_u32_e32 vcc, 0, v12
	v_cndmask_b32_e64 v16, v16, v13, s[4:5]
	v_readlane_b32 s4, v253, 5
	v_addc_co_u32_e32 v0, vcc, v0, v1, vcc
	v_readlane_b32 s5, v253, 6
	v_cmp_ne_u32_e32 vcc, 0, v13
	s_nop 0
	v_cndmask_b32_e64 v16, v16, v14, s[4:5]
	v_cndmask_b32_e64 v1, 0, 1, vcc
	v_cmp_ne_u32_e32 vcc, 0, v14
	v_max_u32_e32 v2, 1, v16
	s_nop 0
	v_addc_co_u32_e32 v0, vcc, v0, v1, vcc
	v_mov_b32_e32 v1, s2
	v_readlane_b32 s2, v251, 34
	v_max_u32_e32 v0, 1, v0
	ds_write_b32 v1, v2
	v_mov_b32_e32 v1, s2
	ds_write_b32 v1, v0
	v_readlane_b32 s4, v253, 3
	v_readlane_b32 s5, v253, 4
	s_nop 4
	global_load_dword v4, v97, s[4:5] offset:-512 sc1
	global_load_dword v5, v97, s[4:5] offset:-448 sc1
	global_load_dword v6, v97, s[4:5] offset:-384 sc1
	global_load_dword v7, v97, s[4:5] offset:-320 sc1
	global_load_dword v8, v97, s[4:5] offset:-256 sc1
	global_load_dword v9, v97, s[4:5] offset:-192 sc1
	global_load_dword v10, v97, s[4:5] offset:-128 sc1
	global_load_dword v11, v97, s[4:5] offset:-64 sc1
	s_waitcnt vmcnt(0)
	v_add_u32_e32 v12, -1, v4
	v_and_b32_e32 v12, v4, v12
	v_mov_b32_e32 v13, v4
	v_add_u32_e32 v14, -1, v5
	v_and_b32_e32 v14, v5, v14
	v_or_b32_e32 v12, v12, v14
	v_min_u32_e32 v13, v13, v5
	v_add_u32_e32 v14, -1, v6
	v_and_b32_e32 v14, v6, v14
	v_or_b32_e32 v12, v12, v14
	v_min_u32_e32 v13, v13, v6
	v_add_u32_e32 v14, -1, v7
	v_and_b32_e32 v14, v7, v14
	v_or_b32_e32 v12, v12, v14
	v_min_u32_e32 v13, v13, v7
	v_add_u32_e32 v14, -1, v8
	v_and_b32_e32 v14, v8, v14
	v_or_b32_e32 v12, v12, v14
	v_min_u32_e32 v13, v13, v8
	v_add_u32_e32 v14, -1, v9
	v_and_b32_e32 v14, v9, v14
	v_or_b32_e32 v12, v12, v14
	v_min_u32_e32 v13, v13, v9
	v_add_u32_e32 v14, -1, v10
	v_and_b32_e32 v14, v10, v14
	v_or_b32_e32 v12, v12, v14
	v_min_u32_e32 v13, v13, v10
	v_add_u32_e32 v14, -1, v11
	v_and_b32_e32 v14, v11, v14
	v_or_b32_e32 v12, v12, v14
	v_min_u32_e32 v13, v13, v11
	v_cmp_eq_u32_e32 vcc, 0, v13
	s_nop 1
	v_cndmask_b32_e64 v14, 0, 1, vcc
	v_or_b32_e32 v12, v12, v14
	v_cmp_eq_u32_e32 vcc, 0, v12
	s_nop 1
	v_cndmask_b32_e64 v12, 0, 1, vcc
	s_nop 1
	v_readfirstlane_b32 s100, v12

.LBB0_611:
	s_andn2_saveexec_b64 s[4:5], s[30:31]
	s_cbranch_execz .LBB0_24
	s_mov_b64 s[30:31], exec
	s_cmp_eq_u32 s100, 0
	s_cbranch_scc1 .Lglobal_bar
	s_cmp_eq_u32 s73, 3
	s_cbranch_scc1 .Llocal_bar
	s_cmp_eq_u32 s73, 5
	s_cbranch_scc1 .Llocal_bar
	s_cmp_eq_u32 s73, 11
	s_cbranch_scc1 .Llocal_bar
	s_cmp_eq_u32 s73, 13
	s_cbranch_scc1 .Llocal_bar
	s_branch .Lglobal_bar
.Llocal_bar:
	buffer_inv sc1
	v_readlane_b32 s4, v253, 39
	v_readlane_b32 s5, v253, 40
	s_nop 4
	global_atomic_add v97, v226, s[4:5]
	s_waitcnt vmcnt(0)
	s_branch .LBB0_24
.Lglobal_bar:
	buffer_wbl2 sc1
	s_waitcnt lgkmcnt(0)
	s_waitcnt vmcnt(0)
	v_mbcnt_lo_u32_b32 v1, s30, 0
	v_mbcnt_hi_u32_b32 v1, s31, v1
	v_cmp_eq_u32_e32 vcc, 0, v1
	s_and_saveexec_b64 s[36:37], vcc
	s_cbranch_execz .LBB0_614
	s_bcnt1_i32_b64 s2, s[30:31]
	v_readlane_b32 s4, v253, 41
	v_mov_b32_e32 v2, s2
	v_readlane_b32 s5, v253, 42
	s_nop 4
	global_atomic_add v2, v97, v2, s[4:5] sc0

	.amdhsa_kernel _Z8mega_fwd4Args
		.amdhsa_group_segment_fixed_size 0
		.amdhsa_private_segment_fixed_size 0
		.amdhsa_kernarg_size 440
		.amdhsa_user_sgpr_count 2
		.amdhsa_user_sgpr_dispatch_ptr 0
		.amdhsa_user_sgpr_queue_ptr 0
		.amdhsa_user_sgpr_kernarg_segment_ptr 1
		.amdhsa_user_sgpr_dispatch_id 0
		.amdhsa_user_sgpr_kernarg_preload_length 0
		.amdhsa_user_sgpr_kernarg_preload_offset 0
		.amdhsa_user_sgpr_private_segment_size 0
		.amdhsa_uses_dynamic_stack 0
		.amdhsa_enable_private_segment 0
		.amdhsa_system_sgpr_workgroup_id_x 1
		.amdhsa_system_sgpr_workgroup_id_y 0
		.amdhsa_system_sgpr_workgroup_id_z 0
		.amdhsa_system_sgpr_workgroup_info 0
		.amdhsa_system_vgpr_workitem_id 2
		.amdhsa_next_free_vgpr 254
		.amdhsa_next_free_sgpr 102
		.amdhsa_accum_offset 256
		.amdhsa_reserve_vcc 1
		.amdhsa_float_round_mode_32 0
		.amdhsa_float_round_mode_16_64 0
		.amdhsa_float_denorm_mode_32 3
		.amdhsa_float_denorm_mode_16_64 3
		.amdhsa_dx10_clamp 1
		.amdhsa_ieee_mode 1
		.amdhsa_fp16_overflow 0
		.amdhsa_tg_split 0
		.amdhsa_exception_fp_ieee_invalid_op 0
		.amdhsa_exception_fp_denorm_src 0
		.amdhsa_exception_fp_ieee_div_zero 0
		.amdhsa_exception_fp_ieee_overflow 0
		.amdhsa_exception_fp_ieee_underflow 0
		.amdhsa_exception_fp_ieee_inexact 0
		.amdhsa_exception_int_div_zero 0
	.end_amdhsa_kernel

amdhsa.kernels:
  - .agpr_count:     0
    .args:
      - .offset:         0
        .size:           184
        .value_kind:     by_value
      - .offset:         184
        .size:           4
        .value_kind:     hidden_block_count_x
      - .offset:         188
        .size:           4
        .value_kind:     hidden_block_count_y
      - .offset:         192
        .size:           4
        .value_kind:     hidden_block_count_z
      - .offset:         196
        .size:           2
        .value_kind:     hidden_group_size_x
      - .offset:         198
        .size:           2
        .value_kind:     hidden_group_size_y
      - .offset:         200
        .size:           2
        .value_kind:     hidden_group_size_z
      - .offset:         202
        .size:           2
        .value_kind:     hidden_remainder_x
      - .offset:         204
        .size:           2
        .value_kind:     hidden_remainder_y
      - .offset:         206
        .size:           2
        .value_kind:     hidden_remainder_z
      - .offset:         224
        .size:           8
        .value_kind:     hidden_global_offset_x
      - .offset:         232
        .size:           8
        .value_kind:     hidden_global_offset_y
      - .offset:         240
        .size:           8
        .value_kind:     hidden_global_offset_z
      - .offset:         248
        .size:           2
        .value_kind:     hidden_grid_dims
      - .offset:         272
        .size:           8
        .value_kind:     hidden_multigrid_sync_arg
      - .offset:         304
        .size:           4
        .value_kind:     hidden_dynamic_lds_size
    .group_segment_fixed_size: 0
    .kernarg_segment_align: 8
    .kernarg_segment_size: 440
    .language:       OpenCL C
    .language_version:
      - 2
      - 0
    .max_flat_workgroup_size: 512
    .name:           _Z8mega_fwd4Args
    .private_segment_fixed_size: 0
    .sgpr_count:     108
    .sgpr_spill_count: 253
    .symbol:         _Z8mega_fwd4Args.kd
    .uniform_work_group_size: 1
    .uses_dynamic_stack: false
    .vgpr_count:     254
    .vgpr_spill_count: 0
    .wavefront_size: 64
